# v32: GLA pass B: wave priority raised for the chunk's MFMA span (s_setprio 1 at the first LDS read, 0 after the last MFMA)
# baseline (speedup 1.0000x reference)
; #define LAS __attribute__((address_space(3)))
; template <bool FULL>
; __device__ __forceinline__ void gla_pass(const Params& P, LAS unsigned char* lds, f32x4 (&S)[8][2], int bh, int c0, int L, bool dry) {
;     ...
;         bf16x8 vf[2][2];
; #pragma unroll
;         for (int vt = 0; vt < 2; ++vt)
; #pragma unroll
;             for (int k2 = 0; k2 < 2; ++k2) vf[vt][k2] = trfrag(Lv, V_P, 32 * k2, (32 * w + 16 * vt) * 2, g, fr);
;         f32x4 o[2][4];
;         if (FULL) {
; #pragma unroll
;             for (int vt = 0; vt < 2; ++vt)
; #pragma unroll
;                 for (int tt = 0; tt < 4; ++tt) o[vt][tt] = (f32x4){0.f, 0.f, 0.f, 0.f};
; #pragma unroll
;             for (int k4 = 0; k4 < 4; ++k4) {
;                 const bf16x8 a0 = rowfrag(Lst, ST_P, 32 * w, 64 * k4, g, fr), a1 = rowfrag(Lst, ST_P, 32 * w + 16, 64 * k4, g, fr);
; #pragma unroll
;                 for (int tt = 0; tt < 4; ++tt) { const bf16x8 bq = rowfrag(Lqd, QD_P, 16 * tt, 64 * k4, g, fr);
;                     o[0][tt] = __builtin_amdgcn_mfma_f32_16x16x32_bf16(a0, bq, o[0][tt], 0, 0, 0); o[1][tt] = __builtin_amdgcn_mfma_f32_16x16x32_bf16(a1, bq, o[1][tt], 0, 0, 0); }
;             }
; #pragma unroll
;             for (int k2 = 0; k2 < 2; ++k2)
; #pragma unroll
;                 for (int tt = 0; tt < 4; ++tt) { const bf16x8 bp = rowfrag(Lp, P_P, 16 * tt, 64 * k2, g, fr);
;                     o[0][tt] = __builtin_amdgcn_mfma_f32_16x16x32_bf16(vf[0][k2], bp, o[0][tt], 0, 0, 0); o[1][tt] = __builtin_amdgcn_mfma_f32_16x16x32_bf16(vf[1][k2], bp, o[1][tt], 0, 0, 0); }
;         }
; #pragma unroll
;         for (int kt = 0; kt < 8; ++kt) { const f32x4 dv = *(const LAS f32x4*)(Ldec + 16 * kt + 4 * g); S[kt][0] = S[kt][0] * dv; S[kt][1] = S[kt][1] * dv; }
.LBB0_703:
	s_setprio 1
	ds_read_b128 v[104:107], v197
	ds_read_b128 v[108:111], v198 offset:18432
	ds_read_b128 v[112:115], v197 offset:64
	ds_read_b128 v[116:119], v198 offset:18496
	ds_read_b128 v[124:127], v197 offset:4352
	ds_read_b128 v[128:131], v197 offset:4416
	ds_read_b128 v[132:135], v198 offset:22784
	ds_read_b128 v[136:139], v198 offset:22848
	ds_read_b128 v[144:147], v198 offset:27136
	ds_read_b128 v[148:151], v198 offset:27200
	ds_read_b128 v[178:181], v198 offset:31488
	ds_read_b128 v[208:211], v198 offset:31552
	s_waitcnt lgkmcnt(10)
	v_mfma_f32_16x16x32_bf16 v[120:123], v[104:107], v[108:111], 0
	v_add_u32_e32 v160, 0x25000, v187
	s_waitcnt lgkmcnt(7)
	v_mfma_f32_16x16x32_bf16 v[108:111], v[124:127], v[108:111], 0
	s_waitcnt lgkmcnt(5)
	v_mfma_f32_16x16x32_bf16 v[140:143], v[104:107], v[132:135], 0
	v_mfma_f32_16x16x32_bf16 v[132:135], v[124:127], v[132:135], 0
	s_waitcnt lgkmcnt(3)
	v_mfma_f32_16x16x32_bf16 v[174:177], v[104:107], v[144:147], 0
	s_waitcnt lgkmcnt(1)
	v_mfma_f32_16x16x32_bf16 v[104:107], v[104:107], v[178:181], 0
	v_mfma_f32_16x16x32_bf16 v[120:123], v[112:115], v[116:119], v[120:123]
	v_mfma_f32_16x16x32_bf16 v[108:111], v[128:131], v[116:119], v[108:111]
	v_mfma_f32_16x16x32_bf16 v[116:119], v[112:115], v[136:139], v[140:143]
	v_mfma_f32_16x16x32_bf16 v[132:135], v[128:131], v[136:139], v[132:135]
	v_mfma_f32_16x16x32_bf16 v[136:139], v[112:115], v[148:151], v[174:177]
	s_waitcnt lgkmcnt(0)
	v_mfma_f32_16x16x32_bf16 v[104:107], v[112:115], v[208:211], v[104:107]
	ds_read_b128 v[112:115], v197 offset:128
	v_mfma_f32_16x16x32_bf16 v[144:147], v[124:127], v[144:147], 0
	v_mfma_f32_16x16x32_bf16 v[124:127], v[124:127], v[178:181], 0
	v_mfma_f32_16x16x32_bf16 v[140:143], v[128:131], v[148:151], v[144:147]
	v_mfma_f32_16x16x32_bf16 v[124:127], v[128:131], v[208:211], v[124:127]
	ds_read_b128 v[128:131], v198 offset:18560
	s_nop 3
	ds_read_b128 v[144:147], v197 offset:192
	ds_read_b128 v[148:151], v198 offset:18624
	ds_read_b128 v[174:177], v197 offset:4480
	ds_read_b128 v[178:181], v197 offset:4544
	s_waitcnt lgkmcnt(4)
	v_mfma_f32_16x16x32_bf16 v[120:123], v[112:115], v[128:131], v[120:123]
	s_waitcnt lgkmcnt(1)
	v_mfma_f32_16x16x32_bf16 v[108:111], v[174:177], v[128:131], v[108:111]
	ds_read_b128 v[128:131], v198 offset:22912
	ds_read_b128 v[208:211], v198 offset:22976
	s_waitcnt lgkmcnt(1)
	v_mfma_f32_16x16x32_bf16 v[116:119], v[112:115], v[128:131], v[116:119]
	v_mfma_f32_16x16x32_bf16 v[128:131], v[174:177], v[128:131], v[132:135]
	s_nop 2
	ds_read_b128 v[132:135], v198 offset:27264
	ds_read_b128 v[212:215], v198 offset:27328
	s_waitcnt lgkmcnt(1)
	v_mfma_f32_16x16x32_bf16 v[136:139], v[112:115], v[132:135], v[136:139]
	v_mfma_f32_16x16x32_bf16 v[132:135], v[174:177], v[132:135], v[140:143]
	s_nop 2
	ds_read_b128 v[140:143], v198 offset:31616
	ds_read_b128 v[216:219], v198 offset:31680
	s_waitcnt lgkmcnt(1)
	v_mfma_f32_16x16x32_bf16 v[104:107], v[112:115], v[140:143], v[104:107]
	v_mfma_f32_16x16x32_bf16 v[112:115], v[174:177], v[140:143], v[124:127]
	v_mfma_f32_16x16x32_bf16 v[120:123], v[144:147], v[148:151], v[120:123]
	v_mfma_f32_16x16x32_bf16 v[108:111], v[178:181], v[148:151], v[108:111]
	v_mfma_f32_16x16x32_bf16 v[116:119], v[144:147], v[208:211], v[116:119]
	v_mfma_f32_16x16x32_bf16 v[124:127], v[178:181], v[208:211], v[128:131]
	v_mfma_f32_16x16x32_bf16 v[128:131], v[144:147], v[212:215], v[136:139]
	s_waitcnt lgkmcnt(0)
	v_mfma_f32_16x16x32_bf16 v[104:107], v[144:147], v[216:219], v[104:107]
	ds_read_b64_tr_b16 v[150:151], v196 offset:38016
	ds_read_b64_tr_b16 v[148:149], v196 offset:35840
	ds_read_b64_tr_b16 v[146:147], v196 offset:38048
	ds_read_b64_tr_b16 v[144:145], v196 offset:35872
	ds_read_b128 v[136:139], v199
	ds_read_b128 v[174:177], v199 offset:64
	v_mfma_f32_16x16x32_bf16 v[132:135], v[178:181], v[212:215], v[132:135]
	v_mfma_f32_16x16x32_bf16 v[112:115], v[178:181], v[216:219], v[112:115]
	s_waitcnt lgkmcnt(1)
	v_mfma_f32_16x16x32_bf16 v[120:123], v[148:151], v[136:139], v[120:123]
	v_mfma_f32_16x16x32_bf16 v[108:111], v[144:147], v[136:139], v[108:111]
	ds_read_b128 v[136:139], v199 offset:2304
	ds_read_b128 v[178:181], v199 offset:2368
	s_waitcnt lgkmcnt(1)
	v_mfma_f32_16x16x32_bf16 v[208:211], v[144:147], v[136:139], v[124:127]
	s_nop 2
	ds_read_b128 v[124:127], v199 offset:4608
	ds_read_b128 v[212:215], v199 offset:4672
	v_mfma_f32_16x16x32_bf16 v[116:119], v[148:151], v[136:139], v[116:119]
	s_waitcnt lgkmcnt(1)
	v_mfma_f32_16x16x32_bf16 v[216:219], v[148:151], v[124:127], v[128:131]
	v_mfma_f32_16x16x32_bf16 v[220:223], v[144:147], v[124:127], v[132:135]
	ds_read_b128 v[124:127], v199 offset:6912
	ds_read_b128 v[224:227], v199 offset:6976
	ds_read_b64_tr_b16 v[140:141], v196 offset:53248
	ds_read_b64_tr_b16 v[142:143], v196 offset:55424
	ds_read_b64_tr_b16 v[138:139], v196 offset:55456
	ds_read_b64_tr_b16 v[136:137], v196 offset:53280
	s_waitcnt lgkmcnt(5)
	v_mfma_f32_16x16x32_bf16 v[228:231], v[148:151], v[124:127], v[104:107]
	v_mfma_f32_16x16x32_bf16 v[112:115], v[144:147], v[124:127], v[112:115]
	s_waitcnt lgkmcnt(2)
	v_mfma_f32_16x16x32_bf16 v[132:135], v[140:143], v[174:177], v[120:123]
	s_waitcnt lgkmcnt(0)
	v_mfma_f32_16x16x32_bf16 v[128:131], v[136:139], v[174:177], v[108:111]
	ds_read_b128 v[174:177], v160
	v_mfma_f32_16x16x32_bf16 v[124:127], v[140:143], v[178:181], v[116:119]
	v_mfma_f32_16x16x32_bf16 v[120:123], v[136:139], v[178:181], v[208:211]
	ds_read_b128 v[178:181], v160 offset:64
	s_waitcnt lgkmcnt(1)
; #define LAS __attribute__((address_space(3)))
; template <bool FULL>
; __device__ __forceinline__ void gla_pass(const Params& P, LAS unsigned char* lds, f32x4 (&S)[8][2], int bh, int c0, int L, bool dry) {
;     ...
; #pragma unroll
;             for (int k2 = 0; k2 < 2; ++k2)
; #pragma unroll
;                 for (int tt = 0; tt < 4; ++tt) { const bf16x8 bp = rowfrag(Lp, P_P, 16 * tt, 64 * k2, g, fr);
;                     o[0][tt] = __builtin_amdgcn_mfma_f32_16x16x32_bf16(vf[0][k2], bp, o[0][tt], 0, 0, 0); o[1][tt] = __builtin_amdgcn_mfma_f32_16x16x32_bf16(vf[1][k2], bp, o[1][tt], 0, 0, 0); }
;         }
; #pragma unroll
;         for (int kt = 0; kt < 8; ++kt) { const f32x4 dv = *(const LAS f32x4*)(Ldec + 16 * kt + 4 * g); S[kt][0] = S[kt][0] * dv; S[kt][1] = S[kt][1] * dv; }
; #pragma unroll
;         for (int k2 = 0; k2 < 2; ++k2)
; #pragma unroll
;             for (int kt = 0; kt < 8; ++kt) { const bf16x8 ak = trfrag(Lks, KS_P, 32 * k2, 32 * kt, g, fr);
;                 S[kt][0] = __builtin_amdgcn_mfma_f32_16x16x32_bf16(ak, vf[0][k2], S[kt][0], 0, 0, 0); S[kt][1] = __builtin_amdgcn_mfma_f32_16x16x32_bf16(ak, vf[1][k2], S[kt][1], 0, 0, 0); }
	v_pk_mul_f32 v[34:35], v[34:35], v[176:177]
	v_pk_mul_f32 v[32:33], v[32:33], v[174:175]
	v_mfma_f32_16x16x32_bf16 v[108:111], v[140:143], v[212:215], v[216:219]
	v_mul_f32_e64 v2, v2, v176
	v_mul_f32_e64 v3, v3, v177
	ds_read_b64_tr_b16 v[210:211], v200 offset:1152
	ds_read_b64_tr_b16 v[208:209], v200
	v_pk_mul_f32 v[0:1], v[0:1], v[174:175]
	v_mfma_f32_16x16x32_bf16 v[104:107], v[136:139], v[212:215], v[220:223]
	ds_read_b64_tr_b16 v[212:213], v200 offset:32
	ds_read_b64_tr_b16 v[216:217], v200 offset:64
	s_nop 0
	ds_read_b64_tr_b16 v[220:221], v200 offset:96
	ds_read_b64_tr_b16 v[214:215], v200 offset:1184
	ds_read_b64_tr_b16 v[218:219], v200 offset:1216
	ds_read_b64_tr_b16 v[222:223], v200 offset:1248
	s_waitcnt lgkmcnt(8)
	v_pk_mul_f32 v[6:7], v[6:7], v[180:181]
	v_pk_mul_f32 v[4:5], v[4:5], v[178:179]
	ds_read_b128 v[174:177], v160 offset:128
	v_pk_mul_f32 v[10:11], v[10:11], v[180:181]
	v_pk_mul_f32 v[8:9], v[8:9], v[178:179]
	ds_read_b128 v[178:181], v160 offset:192
	s_waitcnt lgkmcnt(8)
	v_mfma_f32_16x16x32_bf16 v[32:35], v[208:211], v[148:151], v[32:35]
	s_waitcnt lgkmcnt(1)
	v_pk_mul_f32 v[14:15], v[14:15], v[176:177]
	v_pk_mul_f32 v[12:13], v[12:13], v[174:175]
	v_pk_mul_f32 v[18:19], v[18:19], v[176:177]
	v_pk_mul_f32 v[16:17], v[16:17], v[174:175]
	s_waitcnt lgkmcnt(0)
	v_pk_mul_f32 v[22:23], v[22:23], v[180:181]
	v_pk_mul_f32 v[20:21], v[20:21], v[178:179]
	ds_read_b128 v[174:177], v160 offset:256
	v_pk_mul_f32 v[26:27], v[26:27], v[180:181]
	v_pk_mul_f32 v[24:25], v[24:25], v[178:179]
	ds_read_b128 v[178:181], v160 offset:320
	v_mfma_f32_16x16x32_bf16 v[0:3], v[208:211], v[144:147], v[0:3]
	s_waitcnt lgkmcnt(1)
	v_pk_mul_f32 v[38:39], v[38:39], v[176:177]
	ds_read_b64_tr_b16 v[208:209], v200 offset:128
	ds_read_b64_tr_b16 v[210:211], v200 offset:1280
	v_pk_mul_f32 v[36:37], v[36:37], v[174:175]
	v_mfma_f32_16x16x32_bf16 v[4:7], v[212:215], v[148:151], v[4:7]
	v_mul_f32_e64 v30, v30, v176
	v_mul_f32_e64 v31, v31, v177
	v_pk_mul_f32 v[28:29], v[28:29], v[174:175]
	s_waitcnt lgkmcnt(2)
	v_pk_mul_f32 v[42:43], v[42:43], v[180:181]
	v_mfma_f32_16x16x32_bf16 v[8:11], v[212:215], v[144:147], v[8:11]
	v_mul_f32_e64 v40, v40, v178
	v_mul_f32_e64 v41, v41, v179
	v_pk_mul_f32 v[46:47], v[46:47], v[180:181]
	v_pk_mul_f32 v[44:45], v[44:45], v[178:179]
	v_mfma_f32_16x16x32_bf16 v[12:15], v[216:219], v[148:151], v[12:15]
	v_mfma_f32_16x16x32_bf16 v[16:19], v[216:219], v[144:147], v[16:19]
	v_mfma_f32_16x16x32_bf16 v[20:23], v[220:223], v[148:151], v[20:23]
	v_mfma_f32_16x16x32_bf16 v[24:27], v[220:223], v[144:147], v[24:27]
	ds_read_b64_tr_b16 v[212:213], v200 offset:160
	ds_read_b64_tr_b16 v[216:217], v200 offset:192
	ds_read_b64_tr_b16 v[220:221], v200 offset:224
	ds_read_b64_tr_b16 v[214:215], v200 offset:1312
	ds_read_b64_tr_b16 v[218:219], v200 offset:1344
	ds_read_b64_tr_b16 v[222:223], v200 offset:1376
	ds_read_b128 v[174:177], v160 offset:384
	ds_read_b128 v[178:181], v160 offset:448
	s_waitcnt lgkmcnt(8)
	v_mfma_f32_16x16x32_bf16 v[36:39], v[208:211], v[148:151], v[36:39]
	v_add_u32_e32 v160, s27, v192
	s_waitcnt lgkmcnt(1)
	v_pk_mul_f32 v[50:51], v[50:51], v[176:177]
	v_pk_mul_f32 v[48:49], v[48:49], v[174:175]
	v_pk_mul_f32 v[54:55], v[54:55], v[176:177]
	v_pk_mul_f32 v[52:53], v[52:53], v[174:175]
	s_waitcnt lgkmcnt(0)
	v_pk_mul_f32 v[58:59], v[58:59], v[180:181]
	v_pk_mul_f32 v[56:57], v[56:57], v[178:179]
	v_pk_mul_f32 v[62:63], v[62:63], v[180:181]
	v_pk_mul_f32 v[60:61], v[60:61], v[178:179]
	v_mfma_f32_16x16x32_bf16 v[28:31], v[208:211], v[144:147], v[28:31]
	v_mfma_f32_16x16x32_bf16 v[40:43], v[212:215], v[148:151], v[40:43]
	v_mfma_f32_16x16x32_bf16 v[44:47], v[212:215], v[144:147], v[44:47]
	v_mfma_f32_16x16x32_bf16 v[48:51], v[216:219], v[148:151], v[48:51]
	v_mfma_f32_16x16x32_bf16 v[52:55], v[216:219], v[144:147], v[52:55]
	v_mfma_f32_16x16x32_bf16 v[56:59], v[220:223], v[148:151], v[56:59]
	ds_read_b64_tr_b16 v[148:149], v200 offset:9216
	ds_read_b64_tr_b16 v[150:151], v200 offset:10368
	v_mfma_f32_16x16x32_bf16 v[60:63], v[220:223], v[144:147], v[60:63]
	ds_read_b64_tr_b16 v[144:145], v200 offset:9248
	ds_read_b64_tr_b16 v[174:175], v200 offset:9280
	ds_read_b64_tr_b16 v[178:179], v200 offset:9312
	ds_read_b64_tr_b16 v[146:147], v200 offset:10400
	ds_read_b64_tr_b16 v[176:177], v200 offset:10432
	ds_read_b64_tr_b16 v[180:181], v200 offset:10464
	s_waitcnt lgkmcnt(2)
; template <bool FULL>
; __device__ __forceinline__ void gla_pass(const Params& P, LAS unsigned char* lds, f32x4 (&S)[8][2], int bh, int c0, int L, bool dry) {
;     ...
;         if (FULL) {
; #pragma unroll
;             for (int vt = 0; vt < 2; ++vt)
; #pragma unroll
;                 for (int tt = 0; tt < 4; ++tt) zb[vt][tt] = *(const u32x2*)(PJ + T_ZB + ((size_t)bh * SEQ + n * 64 + 16 * tt + fr) * 256 + 32 * w + 16 * vt + 4 * g);
;         }
;         bf16x8 vf[2][2];
; #pragma unroll
;         for (int vt = 0; vt < 2; ++vt)
; #pragma unroll
;             for (int k2 = 0; k2 < 2; ++k2) vf[vt][k2] = trfrag(Lv, V_P, 32 * k2, (32 * w + 16 * vt) * 2, g, fr);
;         f32x4 o[2][4];
;         if (FULL) {
; #pragma unroll
;             for (int vt = 0; vt < 2; ++vt)
; #pragma unroll
;                 for (int tt = 0; tt < 4; ++tt) o[vt][tt] = (f32x4){0.f, 0.f, 0.f, 0.f};
; #pragma unroll
;             for (int k4 = 0; k4 < 4; ++k4) {
;                 const bf16x8 a0 = rowfrag(Lst, ST_P, 32 * w, 64 * k4, g, fr), a1 = rowfrag(Lst, ST_P, 32 * w + 16, 64 * k4, g, fr);
; #pragma unroll
;                 for (int tt = 0; tt < 4; ++tt) { const bf16x8 bq = rowfrag(Lqd, QD_P, 16 * tt, 64 * k4, g, fr);
;                     o[0][tt] = __builtin_amdgcn_mfma_f32_16x16x32_bf16(a0, bq, o[0][tt], 0, 0, 0); o[1][tt] = __builtin_amdgcn_mfma_f32_16x16x32_bf16(a1, bq, o[1][tt], 0, 0, 0); }
;             }
; #pragma unroll
;             for (int k2 = 0; k2 < 2; ++k2)
; #pragma unroll
;                 for (int tt = 0; tt < 4; ++tt) { const bf16x8 bp = rowfrag(Lp, P_P, 16 * tt, 64 * k2, g, fr);
;                     o[0][tt] = __builtin_amdgcn_mfma_f32_16x16x32_bf16(vf[0][k2], bp, o[0][tt], 0, 0, 0); o[1][tt] = __builtin_amdgcn_mfma_f32_16x16x32_bf16(vf[1][k2], bp, o[1][tt], 0, 0, 0); }
;         }
; #pragma unroll
;         for (int kt = 0; kt < 8; ++kt) { const f32x4 dv = *(const LAS f32x4*)(Ldec + 16 * kt + 4 * g); S[kt][0] = S[kt][0] * dv; S[kt][1] = S[kt][1] * dv; }
; #pragma unroll
;         for (int k2 = 0; k2 < 2; ++k2)
; #pragma unroll
;             for (int kt = 0; kt < 8; ++kt) { const bf16x8 ak = trfrag(Lks, KS_P, 32 * k2, 32 * kt, g, fr);
;                 S[kt][0] = __builtin_amdgcn_mfma_f32_16x16x32_bf16(ak, vf[0][k2], S[kt][0], 0, 0, 0); S[kt][1] = __builtin_amdgcn_mfma_f32_16x16x32_bf16(ak, vf[1][k2], S[kt][1], 0, 0, 0); }
;         if (FULL) {
; #pragma unroll
	v_mfma_f32_16x16x32_bf16 v[4:7], v[144:147], v[140:143], v[4:7]
	v_mfma_f32_16x16x32_bf16 v[8:11], v[144:147], v[136:139], v[8:11]
	ds_read_b64_tr_b16 v[144:145], v200 offset:9344
	ds_read_b64_tr_b16 v[146:147], v200 offset:10496
	ds_read_b64_tr_b16 v[208:209], v200 offset:9376
	ds_read_b64_tr_b16 v[212:213], v200 offset:9408
	ds_read_b64_tr_b16 v[216:217], v200 offset:9440
	ds_read_b64_tr_b16 v[210:211], v200 offset:10528
	ds_read_b64_tr_b16 v[214:215], v200 offset:10560
	ds_read_b64_tr_b16 v[218:219], v200 offset:10592
	v_mfma_f32_16x16x32_bf16 v[32:35], v[148:151], v[140:143], v[32:35]
	v_mfma_f32_16x16x32_bf16 v[0:3], v[148:151], v[136:139], v[0:3]
	v_lshlrev_b64 v[148:149], 9, v[160:161]
	v_lshl_add_u64 v[220:221], v[162:163], 0, v[148:149]
	v_or_b32_e32 v222, 0x2000, v148
	v_mfma_f32_16x16x32_bf16 v[116:119], v[140:143], v[224:227], v[228:231]
	v_mov_b32_e32 v223, v149
	v_lshl_add_u64 v[150:151], v[162:163], 0, v[222:223]
	v_mul_f32_e32 v160, v133, v133
	v_mfma_f32_16x16x32_bf16 v[112:115], v[136:139], v[224:227], v[112:115]
	v_or_b32_e32 v224, 0x4000, v148
	v_or_b32_e32 v148, 0x6000, v148
	v_mov_b32_e32 v225, v149
	s_waitcnt lgkmcnt(9)
	v_mfma_f32_16x16x32_bf16 v[12:15], v[174:177], v[140:143], v[12:15]
	v_lshl_add_u64 v[226:227], v[162:163], 0, v[224:225]
	v_fmac_f32_e32 v160, v132, v132
	v_mfma_f32_16x16x32_bf16 v[16:19], v[174:177], v[136:139], v[16:19]
	v_lshl_add_u64 v[174:175], v[162:163], 0, v[148:149]
	s_waitcnt lgkmcnt(6)
	v_mfma_f32_16x16x32_bf16 v[36:39], v[144:147], v[140:143], v[36:39]
	v_mfma_f32_16x16x32_bf16 v[28:31], v[144:147], v[136:139], v[28:31]
	v_lshl_add_u64 v[144:145], v[164:165], 0, v[222:223]
	v_lshl_add_u64 v[222:223], v[164:165], 0, v[148:149]
	v_mfma_f32_16x16x32_bf16 v[20:23], v[178:181], v[140:143], v[20:23]
	v_mfma_f32_16x16x32_bf16 v[24:27], v[178:181], v[136:139], v[24:27]
	global_load_dwordx2 v[180:181], v[220:221], off
	global_load_dwordx2 v[176:177], v[150:151], off
	s_nop 0
	global_load_dwordx2 v[150:151], v[226:227], off
	global_load_dwordx2 v[178:179], v[220:221], off offset:32
	v_lshl_add_u64 v[220:221], v[164:165], 0, v[224:225]
	global_load_dwordx2 v[146:147], v[174:175], off
	s_nop 0
	global_load_dwordx2 v[174:175], v[144:145], off
	global_load_dwordx2 v[148:149], v[220:221], off
	s_nop 0
	global_load_dwordx2 v[144:145], v[222:223], off
	s_waitcnt lgkmcnt(2)
	v_mfma_f32_16x16x32_bf16 v[40:43], v[208:211], v[140:143], v[40:43]
	v_mfma_f32_16x16x32_bf16 v[44:47], v[208:211], v[136:139], v[44:47]
	v_mul_f32_e32 v208, v135, v135
	v_fmac_f32_e32 v208, v134, v134
	v_add_f32_e32 v160, v160, v208
	v_mul_f32_e32 v208, v129, v129
	v_mul_f32_e32 v209, v131, v131
	v_fmac_f32_e32 v208, v128, v128
	v_fmac_f32_e32 v209, v130, v130
	v_add_f32_e32 v208, v208, v209
	s_waitcnt lgkmcnt(1)
	v_mfma_f32_16x16x32_bf16 v[48:51], v[212:215], v[140:143], v[48:51]
	s_waitcnt lgkmcnt(0)
	v_mfma_f32_16x16x32_bf16 v[56:59], v[216:219], v[140:143], v[56:59]
	v_add_f32_e32 v140, v160, v208
	v_mfma_f32_16x16x32_bf16 v[52:55], v[212:215], v[136:139], v[52:55]
	v_mfma_f32_16x16x32_bf16 v[60:63], v[216:219], v[136:139], v[60:63]
	s_setprio 0
	v_mul_f32_e32 v246, v125, v125
	v_mul_f32_e32 v249, v127, v127
	v_fmac_f32_e32 v246, v124, v124
	v_fmac_f32_e32 v249, v126, v126
	v_add_f32_e32 v246, v246, v249
	v_mul_f32_e32 v249, v121, v121
	v_mul_f32_e32 v250, v123, v123
	v_fmac_f32_e32 v249, v120, v120
	v_fmac_f32_e32 v250, v122, v122
	v_add_f32_e32 v249, v249, v250
	v_add_f32_e32 v246, v246, v249
	v_mul_f32_e32 v247, v109, v109
	v_mul_f32_e32 v249, v111, v111
	v_fmac_f32_e32 v247, v108, v108
	v_fmac_f32_e32 v249, v110, v110
	v_add_f32_e32 v247, v247, v249
	v_mul_f32_e32 v249, v105, v105
	v_mul_f32_e32 v250, v107, v107
	v_fmac_f32_e32 v249, v104, v104
	v_fmac_f32_e32 v250, v106, v106
	v_add_f32_e32 v249, v249, v250
	v_add_f32_e32 v247, v247, v249
	v_mul_f32_e32 v248, v117, v117
	v_mul_f32_e32 v249, v119, v119
	v_fmac_f32_e32 v248, v116, v116
	v_fmac_f32_e32 v249, v118, v118
	v_add_f32_e32 v248, v248, v249
	v_mul_f32_e32 v249, v113, v113
	v_mul_f32_e32 v250, v115, v115
	v_fmac_f32_e32 v249, v112, v112
	v_fmac_f32_e32 v250, v114, v114
	v_add_f32_e32 v249, v249, v250
	v_add_f32_e32 v248, v248, v249
	ds_bpermute_b32 v141, v188, v140
	ds_bpermute_b32 v249, v188, v246
	ds_bpermute_b32 v250, v188, v247
	ds_bpermute_b32 v251, v188, v248
	s_waitcnt lgkmcnt(0)
	v_add_f32_e32 v140, v140, v141
	v_add_f32_e32 v246, v246, v249
	v_add_f32_e32 v247, v247, v250
	v_add_f32_e32 v248, v248, v251
	ds_bpermute_b32 v141, v189, v140
	ds_bpermute_b32 v249, v189, v246
	ds_bpermute_b32 v250, v189, v247
	ds_bpermute_b32 v251, v189, v248
	s_and_saveexec_b64 s[18:19], s[6:7]
	s_cbranch_execz .LBB0_711
	s_waitcnt lgkmcnt(0)
	v_add_f32_e32 v136, v140, v141
	ds_write_b32 v191, v136
	v_add_f32_e32 v136, v246, v249
	ds_write_b32 v191, v136 offset:512
	v_add_f32_e32 v136, v247, v250
	ds_write_b32 v191, v136 offset:1024
	v_add_f32_e32 v136, v248, v251
	ds_write_b32 v191, v136 offset:1536
